# v31 + perm_phase row copy batched (4 row-halves, 8 loads in flight per trip)
# speedup vs baseline: 1.0325x; 1.0051x over previous
; __device__ __forceinline__ void perm_phase(const Params& P, LAS unsigned char* lds, const int tid) {
;     ...
;         for (int idx = wave; idx < 128; idx += 8) { const int t = c * 64 + (idx >> 1); const int d = posl[idx];
;             const u32x4* s = (const u32x4*)((const unsigned char*)H3B + (size_t)t * DM) + lane; u32x4* o = (u32x4*)(XS + (size_t)d * DM) + lane;
;             o[0] = s[0]; o[64] = s[64]; }
.LBB0_4671:
	v_ashrrev_i32_e32 v13, 1, v12
	v_add_u32_e32 v82, 0, v13
	v_add_u32_e32 v14, s16, v82
	v_ashrrev_i32_e32 v15, 31, v14
	v_lshlrev_b64 v[14:15], 11, v[14:15]
	v_lshl_add_u64 v[22:23], v[4:5], 0, v[14:15]
	global_load_dwordx4 v[32:35], v[22:23], off
	global_load_dwordx4 v[36:39], v[22:23], off offset:1024
	ds_read_b32 v64, v11 offset:0
	v_add_u32_e32 v82, 4, v13
	v_add_u32_e32 v14, s16, v82
	v_ashrrev_i32_e32 v15, 31, v14
	v_lshlrev_b64 v[14:15], 11, v[14:15]
	v_lshl_add_u64 v[22:23], v[4:5], 0, v[14:15]
	global_load_dwordx4 v[40:43], v[22:23], off
	global_load_dwordx4 v[44:47], v[22:23], off offset:1024
	ds_read_b32 v65, v11 offset:32
	v_add_u32_e32 v82, 8, v13
	v_add_u32_e32 v14, s16, v82
	v_ashrrev_i32_e32 v15, 31, v14
	v_lshlrev_b64 v[14:15], 11, v[14:15]
	v_lshl_add_u64 v[22:23], v[4:5], 0, v[14:15]
	global_load_dwordx4 v[48:51], v[22:23], off
	global_load_dwordx4 v[52:55], v[22:23], off offset:1024
	ds_read_b32 v66, v11 offset:64
	v_add_u32_e32 v82, 12, v13
	v_add_u32_e32 v14, s16, v82
	v_ashrrev_i32_e32 v15, 31, v14
	v_lshlrev_b64 v[14:15], 11, v[14:15]
	v_lshl_add_u64 v[22:23], v[4:5], 0, v[14:15]
	global_load_dwordx4 v[56:59], v[22:23], off
	global_load_dwordx4 v[60:63], v[22:23], off offset:1024
	ds_read_b32 v67, v11 offset:96
	s_waitcnt lgkmcnt(0)
	v_mov_b32_e32 v80, v64
	v_ashrrev_i32_e32 v81, 31, v80
	v_lshlrev_b64 v[80:81], 11, v[80:81]
	v_lshl_add_u64 v[72:73], v[6:7], 0, v[80:81]
	v_mov_b32_e32 v80, v65
	v_ashrrev_i32_e32 v81, 31, v80
	v_lshlrev_b64 v[80:81], 11, v[80:81]
	v_lshl_add_u64 v[74:75], v[6:7], 0, v[80:81]
	v_mov_b32_e32 v80, v66
	v_ashrrev_i32_e32 v81, 31, v80
	v_lshlrev_b64 v[80:81], 11, v[80:81]
	v_lshl_add_u64 v[76:77], v[6:7], 0, v[80:81]
	v_mov_b32_e32 v80, v67
	v_ashrrev_i32_e32 v81, 31, v80
	v_lshlrev_b64 v[80:81], 11, v[80:81]
	v_lshl_add_u64 v[78:79], v[6:7], 0, v[80:81]
	s_waitcnt vmcnt(6)
	global_store_dwordx4 v[72:73], v[32:35], off
	global_store_dwordx4 v[72:73], v[36:39], off offset:1024
	s_waitcnt vmcnt(6)
	global_store_dwordx4 v[74:75], v[40:43], off
	global_store_dwordx4 v[74:75], v[44:47], off offset:1024
	s_waitcnt vmcnt(6)
	global_store_dwordx4 v[76:77], v[48:51], off
	global_store_dwordx4 v[76:77], v[52:55], off offset:1024
	s_waitcnt vmcnt(6)
	global_store_dwordx4 v[78:79], v[56:59], off
	global_store_dwordx4 v[78:79], v[60:63], off offset:1024
	v_add_u32_e32 v13, 24, v12
	v_cmp_lt_i32_e64 s[4:5], s14, v13
	v_add_u32_e32 v12, 32, v12
	v_add_u32_e32 v11, 0x80, v11
	s_or_b64 s[12:13], s[4:5], s[12:13]
	s_andn2_b64 exec, exec, s[12:13]
	s_cbranch_execnz .LBB0_4671
	s_branch .LBB0_4666
